# cache_tail: bf16 K/V image stores as plain stores (L2 write-combining) instead of 8-byte write-through
# speedup vs baseline: 1.0184x; 1.0170x over previous
.LBB0_421:
	s_or_b64 exec, exec, s[26:27]
	v_lshlrev_b32_e32 v2, 8, v46
	v_lshlrev_b32_e32 v3, 3, v46
	s_mov_b64 s[26:27], -1
	s_cmpk_gt_i32 s38, 0x1fff
	v_and_b32_e32 v38, 0xe00, v2
	v_and_b32_e32 v34, 8, v3
	v_and_b32_e32 v40, 0x800, v2
	v_and_b32_e32 v36, 56, v3
	s_cbranch_scc0 .LBB0_431
	s_load_dwordx4 s[28:31], s[20:21], 0x10
	s_add_i32 s26, s38, 0xffffe000
	v_lshlrev_b32_e32 v2, 2, v46
	v_lshl_add_u32 v2, s26, 10, v2
	v_ashrrev_i32_e32 v3, 31, v2
	v_lshlrev_b64 v[2:3], 2, v[2:3]
	s_waitcnt lgkmcnt(0)
	v_lshl_add_u64 v[42:43], s[28:29], 0, v[2:3]
	v_lshl_add_u64 v[44:45], s[30:31], 0, v[2:3]
	global_load_dwordx4 v[26:29], v[42:43], off
	global_load_dwordx4 v[22:25], v[42:43], off offset:1024
	global_load_dwordx4 v[30:33], v[44:45], off
	global_load_dwordx4 v[18:21], v[44:45], off offset:1024
	global_load_dwordx4 v[10:13], v[42:43], off offset:2048
	global_load_dwordx4 v[6:9], v[42:43], off offset:3072
	global_load_dwordx4 v[14:17], v[44:45], off offset:2048
	global_load_dwordx4 v[2:5], v[44:45], off offset:3072
	v_mov_b32_e32 v41, v35
	v_lshl_add_u32 v47, s26, 8, v46
	v_mov_b32_e32 v39, v35
	v_lshl_add_u64 v[42:43], s[8:9], 0, v[40:41]
	v_lshlrev_b32_e32 v41, 2, v47
	v_lshl_add_u64 v[44:45], s[6:7], 0, v[38:39]
	v_ashrrev_i32_e32 v39, 12, v47
	v_lshrrev_b32_e32 v49, 5, v47
	v_bfe_u32 v54, v41, 6, 1
	v_bfe_u32 v49, v49, 5, 2
	v_lshl_or_b32 v54, v39, 1, v54
	v_mad_i32_i24 v54, v54, 5, v49
	v_ashrrev_i32_e32 v55, 31, v54
	v_bfe_u32 v52, v47, 5, 5
	v_lshlrev_b64 v[54:55], 12, v[54:55]
	v_mov_b32_e32 v51, v35
	v_mov_b32_e32 v53, v35
	v_lshlrev_b32_e32 v50, 4, v52
	v_lshlrev_b32_e32 v52, 6, v52
	v_lshl_add_u64 v[56:57], v[44:45], 0, v[54:55]
	v_lshl_add_u64 v[54:55], v[42:43], 0, v[54:55]
	v_lshl_add_u64 v[50:51], v[56:57], 0, v[50:51]
	v_lshl_add_u64 v[52:53], v[54:55], 0, v[52:53]
	v_bfe_u32 v48, v47, 5, 7
	v_mov_b32_e32 v37, v35
	v_lshl_add_u64 v[50:51], v[50:51], 0, v[34:35]
	v_cmp_lt_u32_e32 vcc, 31, v48
	v_lshl_add_u64 v[52:53], v[52:53], 0, v[36:37]
	s_waitcnt vmcnt(0)
	v_mov_b32_e32 v54, v26
	v_mov_b32_e32 v55, v22
	v_mov_b32_e32 v56, v30
	v_mov_b32_e32 v57, v18
	v_mov_b32_e32 v58, v10
	v_mov_b32_e32 v59, v6
	v_mov_b32_e32 v60, v14
	v_mov_b32_e32 v61, v2
	v_bfe_u32 v49, v26, 16, 1
	v_bfe_u32 v63, v28, 16, 1
	v_pk_add_f32 v[54:55], v[54:55], v[56:57]
	v_bfe_u32 v62, v27, 16, 1
	v_bfe_u32 v64, v29, 16, 1
	v_bfe_u32 v65, v30, 16, 1
	v_bfe_u32 v67, v32, 16, 1
	v_pk_add_f32 v[56:57], v[58:59], v[60:61]
	v_add3_u32 v49, v26, v49, s36
	v_add3_u32 v59, v28, v63, s36
	v_add_f32_e32 v54, 0, v54
	v_bfe_u32 v66, v31, 16, 1
	v_bfe_u32 v68, v33, 16, 1
	v_add3_u32 v58, v27, v62, s36
	v_add3_u32 v60, v29, v64, s36
	v_add3_u32 v61, v30, v65, s36
	v_add3_u32 v63, v32, v67, s36
	v_lshrrev_b32_e32 v49, 16, v49
	v_lshrrev_b32_e32 v59, 16, v59
	v_add_f32_e32 v65, v54, v55
	v_add3_u32 v62, v31, v66, s36
	v_add3_u32 v64, v33, v68, s36
	v_lshrrev_b32_e32 v61, 16, v61
	v_lshrrev_b32_e32 v63, 16, v63
	v_and_or_b32 v54, v58, s37, v49
	v_and_or_b32 v55, v60, s37, v59
	v_add_f32_e32 v49, v65, v56
	v_and_or_b32 v58, v62, s37, v61
	v_and_or_b32 v59, v64, s37, v63
	v_add_f32_e32 v49, v49, v57
	global_store_dwordx2 v[50:51], v[54:55], off
	global_store_dwordx2 v[52:53], v[58:59], off
	s_and_saveexec_b64 s[26:27], vcc
	s_cbranch_execz .LBB0_424
	v_lshl_or_b32 v39, v39, 7, v48
	v_subrev_u32_e32 v48, 32, v39
	v_ashrrev_i32_e32 v49, 31, v48
	v_and_b32_e32 v41, 0x7c, v41
	v_lshlrev_b64 v[48:49], 9, v[48:49]
	v_lshl_or_b32 v48, v41, 2, v48
	v_lshl_add_u64 v[50:51], s[10:11], 0, v[48:49]
	global_store_dwordx4 v[50:51], v[26:29], off sc0 sc1
	s_nop 1
	v_lshl_add_u64 v[26:27], s[12:13], 0, v[48:49]
	global_store_dwordx4 v[26:27], v[30:33], off sc0 sc1
	s_nop 1
.LBB0_424:
	s_or_b64 exec, exec, s[26:27]
	v_add_u32_e32 v29, 64, v47
	v_lshlrev_b32_e32 v27, 2, v29
	v_ashrrev_i32_e32 v26, 12, v29
	v_lshrrev_b32_e32 v30, 5, v29
	v_bfe_u32 v31, v27, 6, 1
	v_lshl_or_b32 v31, v26, 1, v31
	v_bfe_u32 v30, v30, 5, 2
	v_mad_i32_i24 v30, v31, 5, v30
	v_ashrrev_i32_e32 v31, 31, v30
	v_bfe_u32 v39, v22, 16, 1
	v_bfe_u32 v28, v29, 5, 7
	v_lshlrev_b64 v[30:31], 12, v[30:31]
	v_bfe_u32 v29, v29, 5, 5
	v_add3_u32 v39, v22, v39, s36
	v_bfe_u32 v41, v23, 16, 1
	v_lshl_add_u64 v[32:33], v[44:45], 0, v[30:31]
	v_lshlrev_b32_e32 v48, 4, v29
	v_mov_b32_e32 v49, v35
	v_lshrrev_b32_e32 v39, 16, v39
	v_add3_u32 v41, v23, v41, s36
	v_lshl_add_u64 v[32:33], v[32:33], 0, v[48:49]
	v_and_or_b32 v48, v41, s37, v39
	v_bfe_u32 v39, v24, 16, 1
	v_add3_u32 v39, v24, v39, s36
	v_bfe_u32 v41, v25, 16, 1
	v_lshrrev_b32_e32 v39, 16, v39
	v_add3_u32 v41, v25, v41, s36
	v_lshl_add_u64 v[32:33], v[32:33], 0, v[34:35]
	v_and_or_b32 v49, v41, s37, v39
	global_store_dwordx2 v[32:33], v[48:49], off
	v_lshl_add_u64 v[30:31], v[42:43], 0, v[30:31]
	v_lshlrev_b32_e32 v32, 6, v29
	v_mov_b32_e32 v33, v35
	v_bfe_u32 v29, v18, 16, 1
	v_lshl_add_u64 v[30:31], v[30:31], 0, v[32:33]
	v_add3_u32 v29, v18, v29, s36
	v_bfe_u32 v32, v19, 16, 1
	v_lshrrev_b32_e32 v29, 16, v29
	v_add3_u32 v32, v19, v32, s36
	v_and_or_b32 v32, v32, s37, v29
	v_bfe_u32 v29, v20, 16, 1
	v_add3_u32 v29, v20, v29, s36
	v_bfe_u32 v33, v21, 16, 1
	v_lshrrev_b32_e32 v29, 16, v29
	v_add3_u32 v33, v21, v33, s36
	v_lshl_add_u64 v[30:31], v[30:31], 0, v[36:37]
	v_and_or_b32 v33, v33, s37, v29
	v_cmp_lt_u32_e32 vcc, 31, v28
	global_store_dwordx2 v[30:31], v[32:33], off
	s_and_saveexec_b64 s[26:27], vcc
	s_cbranch_execz .LBB0_426
	v_lshl_or_b32 v26, v26, 7, v28
	v_subrev_u32_e32 v26, 32, v26
	v_and_b32_e32 v29, 0x7c, v27
	v_ashrrev_i32_e32 v27, 31, v26
	v_lshlrev_b64 v[26:27], 9, v[26:27]
	v_lshl_or_b32 v26, v29, 2, v26
	v_lshl_add_u64 v[28:29], s[10:11], 0, v[26:27]
	global_store_dwordx4 v[28:29], v[22:25], off sc0 sc1
	s_nop 1
	v_lshl_add_u64 v[22:23], s[12:13], 0, v[26:27]
	global_store_dwordx4 v[22:23], v[18:21], off sc0 sc1
	s_nop 1
.LBB0_426:
	s_or_b64 exec, exec, s[26:27]
	v_add_u32_e32 v21, 0x80, v47
	v_lshlrev_b32_e32 v19, 2, v21
	v_ashrrev_i32_e32 v18, 12, v21
	v_lshrrev_b32_e32 v22, 5, v21
	v_bfe_u32 v23, v19, 6, 1
	v_lshl_or_b32 v23, v18, 1, v23
	v_bfe_u32 v22, v22, 5, 2
	v_mad_i32_i24 v22, v23, 5, v22
	v_ashrrev_i32_e32 v23, 31, v22
	v_bfe_u32 v20, v21, 5, 7
	v_lshlrev_b64 v[22:23], 12, v[22:23]
	v_bfe_u32 v21, v21, 5, 5
	v_lshl_add_u64 v[24:25], v[44:45], 0, v[22:23]
	v_lshlrev_b32_e32 v26, 4, v21
	v_mov_b32_e32 v27, v35
	v_lshl_add_u64 v[24:25], v[24:25], 0, v[26:27]
	v_bfe_u32 v26, v10, 16, 1
	v_add3_u32 v26, v10, v26, s36
	v_bfe_u32 v27, v11, 16, 1
	v_lshrrev_b32_e32 v26, 16, v26
	v_add3_u32 v27, v11, v27, s36
	v_and_or_b32 v26, v27, s37, v26
	v_bfe_u32 v27, v12, 16, 1
	v_add3_u32 v27, v12, v27, s36
	v_bfe_u32 v28, v13, 16, 1
	v_lshrrev_b32_e32 v27, 16, v27
	v_add3_u32 v28, v13, v28, s36
	v_lshl_add_u64 v[24:25], v[24:25], 0, v[34:35]
	v_and_or_b32 v27, v28, s37, v27
	global_store_dwordx2 v[24:25], v[26:27], off
	v_lshl_add_u64 v[22:23], v[42:43], 0, v[22:23]
	v_lshlrev_b32_e32 v24, 6, v21
	v_mov_b32_e32 v25, v35
	v_bfe_u32 v21, v14, 16, 1
	v_lshl_add_u64 v[22:23], v[22:23], 0, v[24:25]
	v_add3_u32 v21, v14, v21, s36
	v_bfe_u32 v24, v15, 16, 1
	v_lshrrev_b32_e32 v21, 16, v21
	v_add3_u32 v24, v15, v24, s36
	v_and_or_b32 v24, v24, s37, v21
	v_bfe_u32 v21, v16, 16, 1
	v_add3_u32 v21, v16, v21, s36
	v_bfe_u32 v25, v17, 16, 1
	v_lshrrev_b32_e32 v21, 16, v21
	v_add3_u32 v25, v17, v25, s36
	v_lshl_add_u64 v[22:23], v[22:23], 0, v[36:37]
	v_and_or_b32 v25, v25, s37, v21
	v_cmp_lt_u32_e32 vcc, 31, v20
	global_store_dwordx2 v[22:23], v[24:25], off
	s_and_saveexec_b64 s[26:27], vcc
	s_cbranch_execz .LBB0_428
	v_lshl_or_b32 v18, v18, 7, v20
	v_subrev_u32_e32 v18, 32, v18
	v_and_b32_e32 v21, 0x7c, v19
	v_ashrrev_i32_e32 v19, 31, v18
	v_lshlrev_b64 v[18:19], 9, v[18:19]
	v_lshl_or_b32 v18, v21, 2, v18
	v_lshl_add_u64 v[20:21], s[10:11], 0, v[18:19]
	global_store_dwordx4 v[20:21], v[10:13], off sc0 sc1
	s_nop 1
	v_lshl_add_u64 v[10:11], s[12:13], 0, v[18:19]
	global_store_dwordx4 v[10:11], v[14:17], off sc0 sc1
	s_nop 1
.LBB0_428:
	s_or_b64 exec, exec, s[26:27]
	v_add_u32_e32 v13, 0xc0, v47
	v_lshlrev_b32_e32 v11, 2, v13
	v_ashrrev_i32_e32 v10, 12, v13
	v_lshrrev_b32_e32 v14, 5, v13
	v_bfe_u32 v15, v11, 6, 1
	v_lshl_or_b32 v15, v10, 1, v15
	v_bfe_u32 v14, v14, 5, 2
	v_mad_i32_i24 v14, v15, 5, v14
	v_ashrrev_i32_e32 v15, 31, v14
	v_bfe_u32 v12, v13, 5, 7
	v_lshlrev_b64 v[14:15], 12, v[14:15]
	v_bfe_u32 v13, v13, 5, 5
	v_lshl_add_u64 v[16:17], v[44:45], 0, v[14:15]
	v_lshlrev_b32_e32 v18, 4, v13
	v_mov_b32_e32 v19, v35
	v_lshl_add_u64 v[16:17], v[16:17], 0, v[18:19]
	v_bfe_u32 v18, v6, 16, 1
	v_add3_u32 v18, v6, v18, s36
	v_bfe_u32 v19, v7, 16, 1
	v_lshrrev_b32_e32 v18, 16, v18
	v_add3_u32 v19, v7, v19, s36
	v_and_or_b32 v18, v19, s37, v18
	v_bfe_u32 v19, v8, 16, 1
	v_add3_u32 v19, v8, v19, s36
	v_bfe_u32 v20, v9, 16, 1
	v_lshrrev_b32_e32 v19, 16, v19
	v_add3_u32 v20, v9, v20, s36
	v_lshl_add_u64 v[16:17], v[16:17], 0, v[34:35]
	v_and_or_b32 v19, v20, s37, v19
	global_store_dwordx2 v[16:17], v[18:19], off
	v_lshl_add_u64 v[14:15], v[42:43], 0, v[14:15]
	v_lshlrev_b32_e32 v16, 6, v13
	v_mov_b32_e32 v17, v35
	v_bfe_u32 v13, v2, 16, 1
	v_lshl_add_u64 v[14:15], v[14:15], 0, v[16:17]
	v_add3_u32 v13, v2, v13, s36
	v_bfe_u32 v16, v3, 16, 1
	v_lshrrev_b32_e32 v13, 16, v13
	v_add3_u32 v16, v3, v16, s36
	v_and_or_b32 v16, v16, s37, v13
	v_bfe_u32 v13, v4, 16, 1
	v_add3_u32 v13, v4, v13, s36
	v_bfe_u32 v17, v5, 16, 1
	v_lshrrev_b32_e32 v13, 16, v13
	v_add3_u32 v17, v5, v17, s36
	v_lshl_add_u64 v[14:15], v[14:15], 0, v[36:37]
	v_and_or_b32 v17, v17, s37, v13
	v_cmp_lt_u32_e32 vcc, 31, v12
	global_store_dwordx2 v[14:15], v[16:17], off
	s_and_saveexec_b64 s[26:27], vcc
	s_cbranch_execz .LBB0_430
	v_lshl_or_b32 v10, v10, 7, v12
	v_subrev_u32_e32 v10, 32, v10
	v_and_b32_e32 v13, 0x7c, v11
	v_ashrrev_i32_e32 v11, 31, v10
	v_lshlrev_b64 v[10:11], 9, v[10:11]
	v_lshl_or_b32 v10, v13, 2, v10
	v_lshl_add_u64 v[12:13], s[10:11], 0, v[10:11]
	global_store_dwordx4 v[12:13], v[6:9], off sc0 sc1
	s_nop 1
	v_lshl_add_u64 v[6:7], s[12:13], 0, v[10:11]
	global_store_dwordx4 v[6:7], v[2:5], off sc0 sc1
	s_nop 1

.LBB0_431:
	s_and_b64 vcc, exec, s[26:27]
	s_cbranch_vccz .LBB0_416
	s_load_dwordx4 s[28:31], s[20:21], 0x20
	s_lshl_b32 s26, s38, 10
	v_lshl_add_u32 v2, v46, 2, s26
	v_ashrrev_i32_e32 v3, 31, v2
	v_lshlrev_b64 v[2:3], 2, v[2:3]
	s_waitcnt lgkmcnt(0)
	v_lshl_add_u64 v[42:43], s[28:29], 0, v[2:3]
	v_lshl_add_u64 v[44:45], s[30:31], 0, v[2:3]
	global_load_dwordx4 v[26:29], v[42:43], off
	global_load_dwordx4 v[22:25], v[42:43], off offset:1024
	global_load_dwordx4 v[30:33], v[44:45], off
	global_load_dwordx4 v[18:21], v[44:45], off offset:1024
	global_load_dwordx4 v[10:13], v[42:43], off offset:2048
	global_load_dwordx4 v[6:9], v[42:43], off offset:3072
	global_load_dwordx4 v[14:17], v[44:45], off offset:2048
	global_load_dwordx4 v[2:5], v[44:45], off offset:3072
	v_lshl_add_u32 v44, s38, 8, v46
	v_mov_b32_e32 v39, v35
	v_mov_b32_e32 v41, v35
	v_lshl_add_u64 v[42:43], s[14:15], 0, v[38:39]
	v_lshl_add_u64 v[38:39], s[18:19], 0, v[40:41]
	v_lshlrev_b32_e32 v41, 2, v44
	v_ashrrev_i32_e32 v40, 16, v44
	v_lshrrev_b32_e32 v46, 7, v44
	v_bfe_u32 v50, v41, 6, 3
	v_bfe_u32 v51, v46, 5, 4
	v_lshl_or_b32 v50, v40, 3, v50
	v_mad_i32_i24 v50, v50, 17, v51
	v_ashrrev_i32_e32 v51, 31, v50
	v_bfe_u32 v48, v44, 7, 5
	v_lshlrev_b64 v[50:51], 12, v[50:51]
	v_mov_b32_e32 v47, v35
	v_mov_b32_e32 v49, v35
	v_lshlrev_b32_e32 v46, 4, v48
	v_lshlrev_b32_e32 v48, 6, v48
	v_lshl_add_u64 v[52:53], v[42:43], 0, v[50:51]
	v_lshl_add_u64 v[50:51], v[38:39], 0, v[50:51]
	v_lshl_add_u64 v[46:47], v[52:53], 0, v[46:47]
	v_lshl_add_u64 v[48:49], v[50:51], 0, v[48:49]
	v_bfe_u32 v45, v44, 7, 9
	v_mov_b32_e32 v37, v35
	v_lshl_add_u64 v[46:47], v[46:47], 0, v[34:35]
	v_cmp_lt_u32_e32 vcc, 31, v45
	v_lshl_add_u64 v[48:49], v[48:49], 0, v[36:37]
	s_waitcnt vmcnt(0)
	v_mov_b32_e32 v50, v26
	v_mov_b32_e32 v51, v22
	v_mov_b32_e32 v52, v30
	v_mov_b32_e32 v53, v18
	v_mov_b32_e32 v54, v10
	v_mov_b32_e32 v55, v6
	v_mov_b32_e32 v56, v14
	v_mov_b32_e32 v57, v2
	v_bfe_u32 v58, v26, 16, 1
	v_bfe_u32 v60, v28, 16, 1
	v_pk_add_f32 v[50:51], v[50:51], v[52:53]
	v_bfe_u32 v59, v27, 16, 1
	v_bfe_u32 v61, v29, 16, 1
	v_bfe_u32 v62, v30, 16, 1
	v_bfe_u32 v64, v32, 16, 1
	v_pk_add_f32 v[52:53], v[54:55], v[56:57]
	v_add3_u32 v54, v26, v58, s36
	v_add3_u32 v56, v28, v60, s36
	v_add_f32_e32 v50, 0, v50
	v_bfe_u32 v63, v31, 16, 1
	v_bfe_u32 v65, v33, 16, 1
	v_add3_u32 v55, v27, v59, s36
	v_add3_u32 v57, v29, v61, s36
	v_add3_u32 v58, v30, v62, s36
	v_add3_u32 v60, v32, v64, s36
	v_lshrrev_b32_e32 v54, 16, v54
	v_lshrrev_b32_e32 v56, 16, v56
	v_add_f32_e32 v62, v50, v51
	v_add3_u32 v59, v31, v63, s36
	v_add3_u32 v61, v33, v65, s36
	v_lshrrev_b32_e32 v58, 16, v58
	v_lshrrev_b32_e32 v60, 16, v60
	v_and_or_b32 v50, v55, s37, v54
	v_and_or_b32 v51, v57, s37, v56
	v_add_f32_e32 v52, v62, v52
	v_and_or_b32 v54, v59, s37, v58
	v_and_or_b32 v55, v61, s37, v60
	v_add_f32_e32 v52, v52, v53
	global_store_dwordx2 v[46:47], v[50:51], off
	global_store_dwordx2 v[48:49], v[54:55], off
	s_and_saveexec_b64 s[26:27], vcc
	s_cbranch_execz .LBB0_434
	v_lshl_or_b32 v40, v40, 9, v45
	v_subrev_u32_e32 v40, 32, v40
	v_and_b32_e32 v46, 0x1fc, v41
	v_ashrrev_i32_e32 v41, 31, v40
	v_lshlrev_b64 v[40:41], 11, v[40:41]
	v_lshl_or_b32 v40, v46, 2, v40
	v_lshl_add_u64 v[46:47], s[24:25], 0, v[40:41]
	global_store_dwordx4 v[46:47], v[26:29], off sc0 sc1
	s_nop 1
	v_lshl_add_u64 v[26:27], s[16:17], 0, v[40:41]
	global_store_dwordx4 v[26:27], v[30:33], off sc0 sc1
	s_nop 1
.LBB0_434:
	s_or_b64 exec, exec, s[26:27]
	v_add_u32_e32 v29, 64, v44
	v_lshlrev_b32_e32 v27, 2, v29
	v_ashrrev_i32_e32 v26, 16, v29
	v_lshrrev_b32_e32 v30, 7, v29
	v_bfe_u32 v31, v27, 6, 3
	v_lshl_or_b32 v31, v26, 3, v31
	v_bfe_u32 v30, v30, 5, 4
	v_mad_i32_i24 v30, v31, 17, v30
	v_ashrrev_i32_e32 v31, 31, v30
	v_bfe_u32 v28, v29, 7, 9
	v_lshlrev_b64 v[30:31], 12, v[30:31]
	v_bfe_u32 v29, v29, 7, 5
	v_lshl_add_u64 v[32:33], v[42:43], 0, v[30:31]
	v_lshlrev_b32_e32 v40, 4, v29
	v_mov_b32_e32 v41, v35
	v_lshl_add_u64 v[32:33], v[32:33], 0, v[40:41]
	v_bfe_u32 v40, v22, 16, 1
	v_add3_u32 v40, v22, v40, s36
	v_bfe_u32 v41, v23, 16, 1
	v_lshrrev_b32_e32 v40, 16, v40
	v_add3_u32 v41, v23, v41, s36
	v_and_or_b32 v40, v41, s37, v40
	v_bfe_u32 v41, v24, 16, 1
	v_add3_u32 v41, v24, v41, s36
	v_bfe_u32 v45, v25, 16, 1
	v_lshrrev_b32_e32 v41, 16, v41
	v_add3_u32 v45, v25, v45, s36
	v_lshl_add_u64 v[32:33], v[32:33], 0, v[34:35]
	v_and_or_b32 v41, v45, s37, v41
	global_store_dwordx2 v[32:33], v[40:41], off
	v_lshl_add_u64 v[30:31], v[38:39], 0, v[30:31]
	v_lshlrev_b32_e32 v32, 6, v29
	v_mov_b32_e32 v33, v35
	v_bfe_u32 v29, v18, 16, 1
	v_lshl_add_u64 v[30:31], v[30:31], 0, v[32:33]
	v_add3_u32 v29, v18, v29, s36
	v_bfe_u32 v32, v19, 16, 1
	v_lshrrev_b32_e32 v29, 16, v29
	v_add3_u32 v32, v19, v32, s36
	v_and_or_b32 v32, v32, s37, v29
	v_bfe_u32 v29, v20, 16, 1
	v_add3_u32 v29, v20, v29, s36
	v_bfe_u32 v33, v21, 16, 1
	v_lshrrev_b32_e32 v29, 16, v29
	v_add3_u32 v33, v21, v33, s36
	v_lshl_add_u64 v[30:31], v[30:31], 0, v[36:37]
	v_and_or_b32 v33, v33, s37, v29
	v_cmp_lt_u32_e32 vcc, 31, v28
	global_store_dwordx2 v[30:31], v[32:33], off
	s_and_saveexec_b64 s[26:27], vcc
	s_cbranch_execz .LBB0_436
	v_lshl_or_b32 v26, v26, 9, v28
	v_subrev_u32_e32 v26, 32, v26
	v_and_b32_e32 v29, 0x1fc, v27
	v_ashrrev_i32_e32 v27, 31, v26
	v_lshlrev_b64 v[26:27], 11, v[26:27]
	v_lshl_or_b32 v26, v29, 2, v26
	v_lshl_add_u64 v[28:29], s[24:25], 0, v[26:27]
	global_store_dwordx4 v[28:29], v[22:25], off sc0 sc1
	s_nop 1
	v_lshl_add_u64 v[22:23], s[16:17], 0, v[26:27]
	global_store_dwordx4 v[22:23], v[18:21], off sc0 sc1
	s_nop 1
.LBB0_436:
	s_or_b64 exec, exec, s[26:27]
	v_add_u32_e32 v21, 0x80, v44
	v_lshlrev_b32_e32 v19, 2, v21
	v_ashrrev_i32_e32 v18, 16, v21
	v_lshrrev_b32_e32 v22, 7, v21
	v_bfe_u32 v23, v19, 6, 3
	v_lshl_or_b32 v23, v18, 3, v23
	v_bfe_u32 v22, v22, 5, 4
	v_mad_i32_i24 v22, v23, 17, v22
	v_ashrrev_i32_e32 v23, 31, v22
	v_bfe_u32 v20, v21, 7, 9
	v_lshlrev_b64 v[22:23], 12, v[22:23]
	v_bfe_u32 v21, v21, 7, 5
	v_lshl_add_u64 v[24:25], v[42:43], 0, v[22:23]
	v_lshlrev_b32_e32 v26, 4, v21
	v_mov_b32_e32 v27, v35
	v_lshl_add_u64 v[24:25], v[24:25], 0, v[26:27]
	v_bfe_u32 v26, v10, 16, 1
	v_add3_u32 v26, v10, v26, s36
	v_bfe_u32 v27, v11, 16, 1
	v_lshrrev_b32_e32 v26, 16, v26
	v_add3_u32 v27, v11, v27, s36
	v_and_or_b32 v26, v27, s37, v26
	v_bfe_u32 v27, v12, 16, 1
	v_add3_u32 v27, v12, v27, s36
	v_bfe_u32 v28, v13, 16, 1
	v_lshrrev_b32_e32 v27, 16, v27
	v_add3_u32 v28, v13, v28, s36
	v_lshl_add_u64 v[24:25], v[24:25], 0, v[34:35]
	v_and_or_b32 v27, v28, s37, v27
	global_store_dwordx2 v[24:25], v[26:27], off
	v_lshl_add_u64 v[22:23], v[38:39], 0, v[22:23]
	v_lshlrev_b32_e32 v24, 6, v21
	v_mov_b32_e32 v25, v35
	v_bfe_u32 v21, v14, 16, 1
	v_lshl_add_u64 v[22:23], v[22:23], 0, v[24:25]
	v_add3_u32 v21, v14, v21, s36
	v_bfe_u32 v24, v15, 16, 1
	v_lshrrev_b32_e32 v21, 16, v21
	v_add3_u32 v24, v15, v24, s36
	v_and_or_b32 v24, v24, s37, v21
	v_bfe_u32 v21, v16, 16, 1
	v_add3_u32 v21, v16, v21, s36
	v_bfe_u32 v25, v17, 16, 1
	v_lshrrev_b32_e32 v21, 16, v21
	v_add3_u32 v25, v17, v25, s36
	v_lshl_add_u64 v[22:23], v[22:23], 0, v[36:37]
	v_and_or_b32 v25, v25, s37, v21
	v_cmp_lt_u32_e32 vcc, 31, v20
	global_store_dwordx2 v[22:23], v[24:25], off
	s_and_saveexec_b64 s[26:27], vcc
	s_cbranch_execz .LBB0_438
	v_lshl_or_b32 v18, v18, 9, v20
	v_subrev_u32_e32 v18, 32, v18
	v_and_b32_e32 v21, 0x1fc, v19
	v_ashrrev_i32_e32 v19, 31, v18
	v_lshlrev_b64 v[18:19], 11, v[18:19]
	v_lshl_or_b32 v18, v21, 2, v18
	v_lshl_add_u64 v[20:21], s[24:25], 0, v[18:19]
	global_store_dwordx4 v[20:21], v[10:13], off sc0 sc1
	s_nop 1
	v_lshl_add_u64 v[10:11], s[16:17], 0, v[18:19]
	global_store_dwordx4 v[10:11], v[14:17], off sc0 sc1
	s_nop 1
.LBB0_438:
	s_or_b64 exec, exec, s[26:27]
	v_add_u32_e32 v13, 0xc0, v44
	v_lshlrev_b32_e32 v11, 2, v13
	v_ashrrev_i32_e32 v10, 16, v13
	v_lshrrev_b32_e32 v14, 7, v13
	v_bfe_u32 v15, v11, 6, 3
	v_lshl_or_b32 v15, v10, 3, v15
	v_bfe_u32 v14, v14, 5, 4
	v_mad_i32_i24 v14, v15, 17, v14
	v_ashrrev_i32_e32 v15, 31, v14
	v_bfe_u32 v12, v13, 7, 9
	v_lshlrev_b64 v[14:15], 12, v[14:15]
	v_bfe_u32 v13, v13, 7, 5
	v_lshl_add_u64 v[16:17], v[42:43], 0, v[14:15]
	v_lshlrev_b32_e32 v18, 4, v13
	v_mov_b32_e32 v19, v35
	v_lshl_add_u64 v[16:17], v[16:17], 0, v[18:19]
	v_bfe_u32 v18, v6, 16, 1
	v_add3_u32 v18, v6, v18, s36
	v_bfe_u32 v19, v7, 16, 1
	v_lshrrev_b32_e32 v18, 16, v18
	v_add3_u32 v19, v7, v19, s36
	v_and_or_b32 v18, v19, s37, v18
	v_bfe_u32 v19, v8, 16, 1
	v_add3_u32 v19, v8, v19, s36
	v_bfe_u32 v20, v9, 16, 1
	v_lshrrev_b32_e32 v19, 16, v19
	v_add3_u32 v20, v9, v20, s36
	v_lshl_add_u64 v[16:17], v[16:17], 0, v[34:35]
	v_and_or_b32 v19, v20, s37, v19
	v_lshlrev_b32_e32 v34, 6, v13
	v_bfe_u32 v13, v2, 16, 1
	global_store_dwordx2 v[16:17], v[18:19], off
	v_add3_u32 v13, v2, v13, s36
	v_bfe_u32 v16, v3, 16, 1
	v_lshrrev_b32_e32 v13, 16, v13
	v_add3_u32 v16, v3, v16, s36
	v_and_or_b32 v16, v16, s37, v13
	v_bfe_u32 v13, v4, 16, 1
	v_lshl_add_u64 v[14:15], v[38:39], 0, v[14:15]
	v_add3_u32 v13, v4, v13, s36
	v_bfe_u32 v17, v5, 16, 1
	v_lshl_add_u64 v[14:15], v[14:15], 0, v[34:35]
	v_lshrrev_b32_e32 v13, 16, v13
	v_add3_u32 v17, v5, v17, s36
	v_lshl_add_u64 v[14:15], v[14:15], 0, v[36:37]
	v_and_or_b32 v17, v17, s37, v13
	v_cmp_lt_u32_e32 vcc, 31, v12
	global_store_dwordx2 v[14:15], v[16:17], off
	s_and_saveexec_b64 s[26:27], vcc
	s_cbranch_execz .LBB0_415
	v_lshl_or_b32 v10, v10, 9, v12
	v_subrev_u32_e32 v10, 32, v10
	v_and_b32_e32 v13, 0x1fc, v11
	v_ashrrev_i32_e32 v11, 31, v10
	v_lshlrev_b64 v[10:11], 11, v[10:11]
	v_lshl_or_b32 v10, v13, 2, v10
	v_lshl_add_u64 v[12:13], s[24:25], 0, v[10:11]
	global_store_dwordx4 v[12:13], v[6:9], off sc0 sc1
	s_nop 1
	v_lshl_add_u64 v[6:7], s[16:17], 0, v[10:11]
	global_store_dwordx4 v[6:7], v[2:5], off sc0 sc1
	s_nop 1
	s_branch .LBB0_415
